# phase_up epilogue staging tile moved into LDS stage 1 (not touched by the next unit's first DMA), unit-end workgroup barrier removed
# speedup vs baseline: 1.0076x; 1.0046x over previous
.LBB0_917:
	v_mov_b32_e32 v139, v5
	s_movk_i32 s70, 0xa00
	s_movk_i32 s71, 0x50
	v_lshrrev_b32_e32 v186, 6, v5
	v_and_b32_e32 v187, 31, v5
	v_bfe_u32 v188, v5, 5, 1
	v_lshlrev_b32_e32 v188, 3, v188
	v_mad_u32_u24 v182, v186, s70, v188
	v_mad_u32_u24 v182, v187, s71, v182
	v_add_u32_e32 v182, 0x10020, v182
	v_and_b32_e32 v187, 63, v5
	v_lshrrev_b32_e32 v188, 2, v187
	v_and_b32_e32 v187, 3, v187
	v_lshlrev_b32_e32 v187, 4, v187
	v_mad_u32_u24 v183, v186, s70, v187
	v_mad_u32_u24 v183, v188, s71, v183
	v_add_u32_e32 v183, 0x10020, v183
	v_lshl_add_u32 v185, v188, 7, v187
	s_movk_i32 s70, 0xc0
	v_mad_u32_u24 v184, v188, s70, v187
	s_cmpk_gt_i32 s12, 0xbf
	s_mov_b64 s[0:1], -1
	s_cbranch_scc0 .LBB0_967
	s_add_i32 s0, s12, 0xffffff40
	v_ashrrev_i32_e32 v1, 6, v139
	v_bfe_u32 v0, v139, 3, 3
	s_lshr_b32 s68, s0, 2
	v_lshl_or_b32 v0, v1, 3, v0
	s_and_b32 s13, s12, 3
	s_lshl_b64 s[0:1], s[68:69], 16
	v_readlane_b32 s4, v254, 27
	v_lshlrev_b32_e32 v20, 10, v1
	v_lshrrev_b32_e32 v1, 1, v0
	v_readlane_b32 s5, v254, 28
	s_add_u32 s0, s4, s0
	v_xor_b32_e32 v6, v1, v139
	v_ashrrev_i32_e32 v1, 31, v0
	s_addc_u32 s1, s5, s1
	v_add_u32_e32 v21, 32, v20
	v_lshlrev_b64 v[0:1], 8, v[0:1]
	v_lshlrev_b32_e32 v6, 4, v6
	s_lshl_b32 s4, s13, 16
	v_lshl_add_u64 v[2:3], s[0:1], 0, v[0:1]
	v_and_b32_e32 v6, 0x70, v6
	v_mov_b32_e32 v7, v4
	v_readfirstlane_b32 s6, v21
	v_add_u32_e32 v10, 0x8000, v21
	s_add_u32 s4, s10, s4
	v_lshl_add_u64 v[2:3], v[2:3], 0, v[6:7]
	s_mov_b32 m0, s6
	v_readfirstlane_b32 s6, v10
	s_addc_u32 s5, s11, 0
	global_load_lds_dwordx4 v[2:3], off
	s_mov_b32 m0, s6
	s_mov_b64 s[6:7], 0x4000
	v_lshl_add_u64 v[8:9], s[4:5], 0, v[0:1]
	v_add_u32_e32 v14, 0x2000, v21
	v_lshl_add_u64 v[10:11], v[0:1], 0, s[6:7]
	v_lshl_add_u64 v[8:9], v[8:9], 0, v[6:7]
	v_lshl_add_u64 v[12:13], s[0:1], 0, v[10:11]
	v_readfirstlane_b32 s6, v14
	v_add_u32_e32 v14, 0xa000, v21
	global_load_lds_dwordx4 v[8:9], off
	v_lshl_add_u64 v[12:13], v[12:13], 0, v[6:7]
	s_mov_b32 m0, s6
	v_readfirstlane_b32 s6, v14
	global_load_lds_dwordx4 v[12:13], off
	s_mov_b32 m0, s6
	s_mov_b64 s[6:7], 0x8000
	v_lshl_add_u64 v[10:11], s[4:5], 0, v[10:11]
	v_add_u32_e32 v18, 0x4000, v21
	v_lshl_add_u64 v[14:15], v[0:1], 0, s[6:7]
	v_lshl_add_u64 v[10:11], v[10:11], 0, v[6:7]
	v_lshl_add_u64 v[16:17], s[0:1], 0, v[14:15]
	v_readfirstlane_b32 s6, v18
	v_add_u32_e32 v18, 0xc000, v21
	global_load_lds_dwordx4 v[10:11], off
	v_lshl_add_u64 v[16:17], v[16:17], 0, v[6:7]
	s_mov_b32 m0, s6
	v_readfirstlane_b32 s6, v18
	global_load_lds_dwordx4 v[16:17], off
	s_mov_b32 m0, s6
	s_mov_b64 s[6:7], 0xc000
	v_lshl_add_u64 v[0:1], v[0:1], 0, s[6:7]
	v_lshl_add_u64 v[14:15], s[4:5], 0, v[14:15]
	v_add_u32_e32 v22, 0x6000, v21
	v_lshl_add_u64 v[18:19], s[0:1], 0, v[0:1]
	v_lshl_add_u64 v[0:1], s[4:5], 0, v[0:1]
	v_lshl_add_u64 v[14:15], v[14:15], 0, v[6:7]
	v_lshl_add_u64 v[18:19], v[18:19], 0, v[6:7]
	v_readfirstlane_b32 s0, v22
	v_lshl_add_u64 v[0:1], v[0:1], 0, v[6:7]
	v_add_u32_e32 v6, 0xe000, v21
	global_load_lds_dwordx4 v[14:15], off
	s_mov_b32 m0, s0
	v_readfirstlane_b32 s0, v6
	v_lshrrev_b32_e32 v6, 5, v139
	v_bfe_u32 v148, v139, 1, 3
	v_bitop3_b32 v6, v6, v148, 1 bitop3:0x6c
	global_load_lds_dwordx4 v[18:19], off
	s_mov_b32 m0, s0
	v_lshlrev_b32_e32 v149, 4, v6
	v_lshlrev_b32_e32 v6, 7, v139
	s_add_i32 s0, 32, 0x10000
	v_and_b32_e32 v150, 0x6f80, v6
	v_add_u32_e32 v6, s0, v20
	global_load_lds_dwordx4 v[0:1], off
	v_readfirstlane_b32 s1, v6
	v_lshl_add_u64 v[2:3], v[2:3], 0, s[54:55]
	s_mov_b32 m0, s1
	s_waitcnt vmcnt(0)
	s_waitcnt vmcnt(0) lgkmcnt(0)
	s_barrier
	global_load_lds_dwordx4 v[2:3], off
	v_lshl_add_u64 v[2:3], v[8:9], 0, s[54:55]
	v_add_u32_e32 v8, 0x8000, v6
	v_and_b32_e32 v152, 31, v139
	v_readfirstlane_b32 s1, v8
	v_add_u32_e32 v8, 0x2000, v6
	s_mov_b32 m0, s1
	v_readfirstlane_b32 s1, v8
	v_add_u32_e32 v8, 0xa000, v6
	global_load_lds_dwordx4 v[2:3], off
	v_lshl_add_u64 v[2:3], v[12:13], 0, s[54:55]
	s_mov_b32 m0, s1
	v_readfirstlane_b32 s1, v8
	v_add_u32_e32 v8, 0x4000, v6
	global_load_lds_dwordx4 v[2:3], off
	v_lshl_add_u64 v[2:3], v[10:11], 0, s[54:55]
	s_mov_b32 m0, s1
	v_readfirstlane_b32 s1, v8
	v_add_u32_e32 v8, 0xc000, v6
	global_load_lds_dwordx4 v[2:3], off
	v_lshl_add_u64 v[2:3], v[16:17], 0, s[54:55]
	s_mov_b32 m0, s1
	v_readfirstlane_b32 s1, v8
	v_add_u32_e32 v8, 0x6000, v6
	global_load_lds_dwordx4 v[2:3], off
	v_lshl_add_u64 v[2:3], v[14:15], 0, s[54:55]
	s_mov_b32 m0, s1
	v_readfirstlane_b32 s1, v8
	global_load_lds_dwordx4 v[2:3], off
	v_lshl_add_u64 v[2:3], v[18:19], 0, s[54:55]
	s_mov_b32 m0, s1
	v_lshrrev_b32_e32 v7, 1, v139
	global_load_lds_dwordx4 v[2:3], off
	v_add_u32_e32 v2, 0xe000, v6
	v_lshl_add_u64 v[0:1], v[0:1], 0, s[54:55]
	v_readfirstlane_b32 s1, v2
	s_mov_b32 m0, s1
	s_mov_b32 s1, 0x1ffff80
	v_and_or_b32 v7, v7, s1, v152
	v_add_u32_e32 v6, 32, v149
	v_lshlrev_b32_e32 v151, 7, v7
	global_load_lds_dwordx4 v[0:1], off
	v_add_u32_e32 v10, v6, v150
	v_add_u32_e32 v14, v6, v151
	ds_read_b128 v[0:3], v10 offset:32768
	ds_read_b128 v[6:9], v14
	ds_read_b128 v[10:13], v10 offset:36864
	s_waitcnt lgkmcnt(0)
	v_mfma_f32_32x32x16_bf16 v[118:133], v[0:3], v[6:9], 0
	v_bfe_u32 v153, v139, 5, 1
	s_add_i32 s1, 32, 0x18000
	v_mfma_f32_32x32x16_bf16 v[102:117], v[10:13], v[6:9], 0
	ds_read_b128 v[6:9], v14 offset:4096
	s_waitcnt lgkmcnt(0)
	v_mfma_f32_32x32x16_bf16 v[86:101], v[0:3], v[6:9], 0
	v_mfma_f32_32x32x16_bf16 v[70:85], v[10:13], v[6:9], 0
	ds_read_b128 v[6:9], v14 offset:8192
	s_waitcnt lgkmcnt(0)
	v_mfma_f32_32x32x16_bf16 v[54:69], v[0:3], v[6:9], 0
	v_mfma_f32_32x32x16_bf16 v[38:53], v[10:13], v[6:9], 0
	ds_read_b128 v[6:9], v14 offset:12288
	s_waitcnt lgkmcnt(0)
	v_mfma_f32_32x32x16_bf16 v[22:37], v[0:3], v[6:9], 0
	v_bitop3_b32 v0, v153, v148, 2 bitop3:0x36
	v_lshlrev_b32_e32 v154, 4, v0
	v_add_u32_e32 v134, 32, v154
	v_add_u32_e32 v144, v134, v150
	v_add_u32_e32 v155, v134, v151
	ds_read_b128 v[0:3], v144 offset:32768
	ds_read_b128 v[134:137], v155
	ds_read_b128 v[144:147], v144 offset:36864
	s_waitcnt lgkmcnt(0)
	v_mfma_f32_32x32x16_bf16 v[118:133], v[0:3], v[134:137], v[118:133]
	v_mfma_f32_32x32x16_bf16 v[102:117], v[144:147], v[134:137], v[102:117]
	ds_read_b128 v[134:137], v155 offset:4096
	s_waitcnt lgkmcnt(0)
	v_mfma_f32_32x32x16_bf16 v[86:101], v[0:3], v[134:137], v[86:101]
	v_mfma_f32_32x32x16_bf16 v[70:85], v[144:147], v[134:137], v[70:85]
	ds_read_b128 v[134:137], v155 offset:8192
	v_mfma_f32_32x32x16_bf16 v[6:21], v[10:13], v[6:9], 0
	s_waitcnt lgkmcnt(0)
	v_mfma_f32_32x32x16_bf16 v[54:69], v[0:3], v[134:137], v[54:69]
	v_mfma_f32_32x32x16_bf16 v[38:53], v[144:147], v[134:137], v[38:53]
	ds_read_b128 v[134:137], v155 offset:12288
	s_waitcnt lgkmcnt(0)
	v_mfma_f32_32x32x16_bf16 v[22:37], v[0:3], v[134:137], v[22:37]
	v_bitop3_b32 v0, v153, v148, 4 bitop3:0x36
	v_lshlrev_b32_e32 v155, 4, v0
	v_mfma_f32_32x32x16_bf16 v[6:21], v[144:147], v[134:137], v[6:21]
	v_add_u32_e32 v134, 32, v155
	v_add_u32_e32 v144, v134, v150
	v_add_u32_e32 v156, v134, v151
	ds_read_b128 v[0:3], v144 offset:32768
	ds_read_b128 v[134:137], v156
	ds_read_b128 v[144:147], v144 offset:36864
	s_waitcnt lgkmcnt(0)
	v_mfma_f32_32x32x16_bf16 v[118:133], v[0:3], v[134:137], v[118:133]
	v_mfma_f32_32x32x16_bf16 v[102:117], v[144:147], v[134:137], v[102:117]
	ds_read_b128 v[134:137], v156 offset:4096
	s_waitcnt lgkmcnt(0)
	v_mfma_f32_32x32x16_bf16 v[86:101], v[0:3], v[134:137], v[86:101]
	v_mfma_f32_32x32x16_bf16 v[70:85], v[144:147], v[134:137], v[70:85]
	ds_read_b128 v[134:137], v156 offset:8192
	s_waitcnt lgkmcnt(0)
	v_mfma_f32_32x32x16_bf16 v[54:69], v[0:3], v[134:137], v[54:69]
	v_mfma_f32_32x32x16_bf16 v[38:53], v[144:147], v[134:137], v[38:53]
	ds_read_b128 v[134:137], v156 offset:12288
	s_waitcnt lgkmcnt(0)
	v_mfma_f32_32x32x16_bf16 v[22:37], v[0:3], v[134:137], v[22:37]
	v_bitop3_b32 v0, v153, v148, 6 bitop3:0x36
	v_lshlrev_b32_e32 v148, 4, v0
	v_mfma_f32_32x32x16_bf16 v[6:21], v[144:147], v[134:137], v[6:21]
	v_add_u32_e32 v134, 32, v148
	v_add_u32_e32 v144, v134, v150
	v_add_u32_e32 v153, v134, v151
	ds_read_b128 v[0:3], v144 offset:32768
	ds_read_b128 v[134:137], v153
	ds_read_b128 v[144:147], v144 offset:36864
	s_waitcnt lgkmcnt(0)
	v_mfma_f32_32x32x16_bf16 v[118:133], v[0:3], v[134:137], v[118:133]
	v_mfma_f32_32x32x16_bf16 v[102:117], v[144:147], v[134:137], v[102:117]
	ds_read_b128 v[134:137], v153 offset:4096
	s_waitcnt lgkmcnt(0)
	v_mfma_f32_32x32x16_bf16 v[86:101], v[0:3], v[134:137], v[86:101]
	v_mfma_f32_32x32x16_bf16 v[70:85], v[144:147], v[134:137], v[70:85]
	ds_read_b128 v[134:137], v153 offset:8192
	s_waitcnt lgkmcnt(0)
	v_mfma_f32_32x32x16_bf16 v[54:69], v[0:3], v[134:137], v[54:69]
	v_mfma_f32_32x32x16_bf16 v[38:53], v[144:147], v[134:137], v[38:53]
	ds_read_b128 v[134:137], v153 offset:12288
	s_waitcnt vmcnt(0)
	s_waitcnt vmcnt(0) lgkmcnt(0)
	s_barrier
	v_mfma_f32_32x32x16_bf16 v[6:21], v[144:147], v[134:137], v[6:21]
	v_add3_u32 v144, s1, v149, v150
	v_add3_u32 v149, s0, v149, v151
	v_mfma_f32_32x32x16_bf16 v[22:37], v[0:3], v[134:137], v[22:37]
	ds_read_b128 v[0:3], v144
	ds_read_b128 v[134:137], v149
	ds_read_b128 v[144:147], v144 offset:4096
	s_waitcnt lgkmcnt(1)
	v_mfma_f32_32x32x16_bf16 v[118:133], v[0:3], v[134:137], v[118:133]
	s_waitcnt lgkmcnt(0)
	v_mfma_f32_32x32x16_bf16 v[102:117], v[144:147], v[134:137], v[102:117]
	ds_read_b128 v[134:137], v149 offset:4096
	s_waitcnt lgkmcnt(0)
	v_mfma_f32_32x32x16_bf16 v[86:101], v[0:3], v[134:137], v[86:101]
	v_mfma_f32_32x32x16_bf16 v[70:85], v[144:147], v[134:137], v[70:85]
	ds_read_b128 v[134:137], v149 offset:8192
	s_waitcnt lgkmcnt(0)
	v_mfma_f32_32x32x16_bf16 v[54:69], v[0:3], v[134:137], v[54:69]
	v_mfma_f32_32x32x16_bf16 v[38:53], v[144:147], v[134:137], v[38:53]
	ds_read_b128 v[134:137], v149 offset:12288
	v_add3_u32 v149, s0, v154, v151
	s_waitcnt lgkmcnt(0)
	v_mfma_f32_32x32x16_bf16 v[6:21], v[144:147], v[134:137], v[6:21]
	v_add3_u32 v144, s1, v154, v150
	v_mfma_f32_32x32x16_bf16 v[22:37], v[0:3], v[134:137], v[22:37]
	ds_read_b128 v[0:3], v144
	ds_read_b128 v[134:137], v149
	ds_read_b128 v[144:147], v144 offset:4096
	s_waitcnt lgkmcnt(1)
	v_mfma_f32_32x32x16_bf16 v[118:133], v[0:3], v[134:137], v[118:133]
	s_waitcnt lgkmcnt(0)
	v_mfma_f32_32x32x16_bf16 v[102:117], v[144:147], v[134:137], v[102:117]
	ds_read_b128 v[134:137], v149 offset:4096
	s_waitcnt lgkmcnt(0)
	v_mfma_f32_32x32x16_bf16 v[86:101], v[0:3], v[134:137], v[86:101]
	v_mfma_f32_32x32x16_bf16 v[70:85], v[144:147], v[134:137], v[70:85]
	ds_read_b128 v[134:137], v149 offset:8192
	s_waitcnt lgkmcnt(0)
	v_mfma_f32_32x32x16_bf16 v[54:69], v[0:3], v[134:137], v[54:69]
	v_mfma_f32_32x32x16_bf16 v[38:53], v[144:147], v[134:137], v[38:53]
	ds_read_b128 v[134:137], v149 offset:12288
	v_add3_u32 v149, s0, v155, v151
	s_waitcnt lgkmcnt(0)
	v_mfma_f32_32x32x16_bf16 v[6:21], v[144:147], v[134:137], v[6:21]
	v_add3_u32 v144, s1, v155, v150
	v_mfma_f32_32x32x16_bf16 v[22:37], v[0:3], v[134:137], v[22:37]
	ds_read_b128 v[0:3], v144
	ds_read_b128 v[134:137], v149
	ds_read_b128 v[144:147], v144 offset:4096
	s_waitcnt lgkmcnt(1)
	v_mfma_f32_32x32x16_bf16 v[118:133], v[0:3], v[134:137], v[118:133]
	s_waitcnt lgkmcnt(0)
	v_mfma_f32_32x32x16_bf16 v[102:117], v[144:147], v[134:137], v[102:117]
	ds_read_b128 v[134:137], v149 offset:4096
	s_waitcnt lgkmcnt(0)
	v_mfma_f32_32x32x16_bf16 v[86:101], v[0:3], v[134:137], v[86:101]
	v_mfma_f32_32x32x16_bf16 v[70:85], v[144:147], v[134:137], v[70:85]
	ds_read_b128 v[134:137], v149 offset:8192
	s_waitcnt lgkmcnt(0)
	v_mfma_f32_32x32x16_bf16 v[54:69], v[0:3], v[134:137], v[54:69]
	v_mfma_f32_32x32x16_bf16 v[38:53], v[144:147], v[134:137], v[38:53]
	ds_read_b128 v[134:137], v149 offset:12288
	s_waitcnt lgkmcnt(0)
	v_mfma_f32_32x32x16_bf16 v[6:21], v[144:147], v[134:137], v[6:21]
	v_add3_u32 v144, s1, v148, v150
	ds_read_b128 v[154:157], v144 offset:4096
	v_add3_u32 v145, s0, v148, v151
	s_movk_i32 s0, 0x9f
	v_mfma_f32_32x32x16_bf16 v[22:37], v[0:3], v[134:137], v[22:37]
	ds_read_b128 v[0:3], v144
	ds_read_b128 v[134:137], v145
	s_waitcnt lgkmcnt(0)
	v_mfma_f32_32x32x16_bf16 v[118:133], v[0:3], v[134:137], v[118:133]
	v_mfma_f32_32x32x16_bf16 v[102:117], v[154:157], v[134:137], v[102:117]
	ds_read_b128 v[134:137], v145 offset:4096
	ds_read_b128 v[148:151], v145 offset:8192
	ds_read_b128 v[158:161], v145 offset:12288
	s_waitcnt vmcnt(0)
	s_waitcnt lgkmcnt(0)
	s_barrier
	v_mfma_f32_32x32x16_bf16 v[86:101], v[0:3], v[134:137], v[86:101]
	v_mfma_f32_32x32x16_bf16 v[70:85], v[154:157], v[134:137], v[70:85]
	v_ashrrev_i32_e32 v134, 1, v139
	v_and_b32_e32 v134, 0xffffff80, v134
	v_or_b32_e32 v135, v134, v152
	v_lshl_add_u32 v144, s68, 8, v135
	v_bitop3_b32 v146, v134, s0, v152 bitop3:0xc8
	v_subrev_co_u32_e32 v134, vcc, 0x4000, v144
	v_mfma_f32_32x32x16_bf16 v[54:69], v[0:3], v[148:151], v[54:69]
	v_lshrrev_b32_e32 v137, 9, v134
	v_and_b32_e32 v134, 0x19f, v144
	v_ashrrev_i32_e32 v136, 8, v144
	s_mov_b64 s[4:5], vcc
	v_cmp_lt_i32_e64 s[6:7], s89, v144
	v_mov_b32_e32 v152, v146
	v_mov_b32_e32 v145, v136
	v_mfma_f32_32x32x16_bf16 v[38:53], v[154:157], v[148:151], v[38:53]
	v_or_b32_e32 v149, 0x1000, v134
	v_add_u32_e32 v134, 0xffffe000, v144
	v_lshrrev_b32_e32 v150, 12, v134
	v_and_b32_e32 v151, 0xf9f, v144
	v_mov_b64_e32 v[134:135], 0xc952000
	v_cndmask_b32_e64 v147, v149, v151, s[4:5]
	v_cndmask_b32_e64 v148, v137, v150, s[4:5]
	v_mfma_f32_32x32x16_bf16 v[22:37], v[0:3], v[158:161], v[22:37]
	v_mov_b64_e32 v[2:3], 0x100
	v_mov_b64_e32 v[0:1], 0xdb62000
	v_mfma_f32_32x32x16_bf16 v[6:21], v[154:157], v[158:161], v[6:21]
	s_and_saveexec_b64 s[0:1], s[6:7]
	v_cndmask_b32_e64 v152, v149, v151, s[4:5]
	v_cndmask_b32_e64 v145, v137, v150, s[4:5]
	v_mov_b64_e32 v[2:3], 0x1200
	v_mov_b64_e32 v[134:135], 0xd152000
	v_mov_b64_e32 v[0:1], 0xe362000
	s_or_b64 exec, exec, s[0:1]
	v_lshrrev_b32_e32 v3, 3, v139
	v_and_b32_e32 v137, 0x80, v139
	v_lshl_or_b32 v137, s13, 8, v137
	v_and_b32_e32 v151, 4, v3
	v_or_b32_e32 v149, 0xffffffc0, v151
	v_lshrrev_b32_e32 v137, 7, v137
	v_and_b32_e32 v150, 64, v139
	v_lshl_or_b32 v3, v145, 3, v137
	v_cmp_ne_u32_e32 vcc, 0, v150
	v_add_u32_e32 v145, v149, v150
	s_and_saveexec_b64 s[0:1], vcc
	s_xor_b64 s[0:1], exec, s[0:1]
	s_cbranch_execz .LBB0_922
	v_mad_i64_i32 v[134:135], s[14:15], v2, v3, 0
	v_lshl_add_u64 v[0:1], s[26:27], 0, v[0:1]
	v_lshlrev_b64 v[134:135], 7, v[134:135]
	v_lshl_add_u64 v[0:1], v[0:1], 0, v[134:135]
	v_mad_u64_u32 v[134:135], s[14:15], v2, v145, 0
	v_lshl_add_u64 v[0:1], v[134:135], 1, v[0:1]
	v_lshlrev_b32_e32 v134, 1, v152
	v_mov_b32_e32 v135, v4
	v_lshl_add_u64 v[0:1], v[0:1], 0, v[134:135]
	v_cvt_pk_bf16_f32 v3, v118, s0
	global_store_short v[0:1], v3, off
	v_cvt_pk_bf16_f32 v3, v119, s0
	v_lshlrev_b32_e32 v118, 1, v2
	v_mov_b32_e32 v119, v4
	v_lshl_add_u64 v[0:1], v[0:1], 0, v[118:119]
	global_store_short v[0:1], v3, off
	v_cvt_pk_bf16_f32 v3, v120, s0
	v_lshl_add_u64 v[0:1], v[0:1], 0, v[118:119]
	global_store_short v[0:1], v3, off
	v_cvt_pk_bf16_f32 v3, v121, s0
	v_lshl_add_u64 v[0:1], v[0:1], 0, v[118:119]
	global_store_short v[0:1], v3, off
	v_cvt_pk_bf16_f32 v3, v122, s0
	v_mad_u64_u32 v[0:1], s[14:15], v2, 10, v[0:1]
	global_store_short v[0:1], v3, off
	v_cvt_pk_bf16_f32 v3, v123, s0
	v_lshl_add_u64 v[0:1], v[0:1], 0, v[118:119]
	global_store_short v[0:1], v3, off
	v_cvt_pk_bf16_f32 v3, v124, s0
	v_lshl_add_u64 v[0:1], v[0:1], 0, v[118:119]
	global_store_short v[0:1], v3, off
	v_cvt_pk_bf16_f32 v3, v125, s0
	v_lshl_add_u64 v[0:1], v[0:1], 0, v[118:119]
	global_store_short v[0:1], v3, off
	v_cvt_pk_bf16_f32 v3, v126, s0
	v_mad_u64_u32 v[0:1], s[14:15], v2, 10, v[0:1]
	global_store_short v[0:1], v3, off
	v_cvt_pk_bf16_f32 v3, v127, s0
	v_lshl_add_u64 v[0:1], v[0:1], 0, v[118:119]
	global_store_short v[0:1], v3, off
	v_cvt_pk_bf16_f32 v3, v128, s0
	v_lshl_add_u64 v[0:1], v[0:1], 0, v[118:119]
	global_store_short v[0:1], v3, off
	v_cvt_pk_bf16_f32 v3, v129, s0
	v_lshl_add_u64 v[0:1], v[0:1], 0, v[118:119]
	global_store_short v[0:1], v3, off
	v_cvt_pk_bf16_f32 v3, v130, s0
	v_mad_u64_u32 v[0:1], s[14:15], v2, 10, v[0:1]
	global_store_short v[0:1], v3, off
	v_cvt_pk_bf16_f32 v2, v131, s0
	v_lshl_add_u64 v[0:1], v[0:1], 0, v[118:119]
	global_store_short v[0:1], v2, off
	v_cvt_pk_bf16_f32 v2, v132, s0
	v_lshl_add_u64 v[0:1], v[0:1], 0, v[118:119]
	global_store_short v[0:1], v2, off
	v_cvt_pk_bf16_f32 v2, v133, s0
	v_lshl_add_u64 v[0:1], v[0:1], 0, v[118:119]
	global_store_short v[0:1], v2, off
